# batch-affine S5 units and cumsums; seams 1-5 stop at the XCC level when every blockIdx%8 class sits on one XCC (checked at run time, full barrier otherwise)
# speedup vs baseline: 1.0370x; 1.0370x over previous
.Ltok_done:
	buffer_inv sc1
	s_lshl_b32 s8, s33, 8
	v_mov_b32_e32 v0, s8
	v_mov_b32_e32 v1, 1
	global_atomic_add v0, v1, s[92:93] offset:1024
	s_and_b32 s100, s2, 7
	s_lshl_b32 s100, s100, 2
	s_lshl_b32 s101, 1, s33
	v_mov_b32_e32 v3, s100
	v_mov_b32_e32 v4, s101
	global_atomic_or v3, v4, s[92:93]
	s_mov_b32 s100, 0
	v_mov_b32_e32 v0, s94
	s_waitcnt vmcnt(0) expcnt(0) lgkmcnt(0)
	ds_read_b32 v2, v0
	ds_read_b32 v0, v0 offset:4
	s_waitcnt lgkmcnt(1)
	v_cmp_ne_u32_e32 vcc, 0, v2
	s_cbranch_vccnz .LBB0_123
	s_add_u32 s0, s70, 0x4200
	s_addc_u32 s1, s71, 0
	s_add_u32 s8, s70, 0x4400
	s_addc_u32 s9, s71, 0
	s_add_u32 s12, s70, 0x4500
	s_addc_u32 s13, s71, 0
	s_add_u32 s14, s70, 0x4600
	s_addc_u32 s15, s71, 0
	s_add_u32 s16, s70, 0x4700
	s_addc_u32 s17, s71, 0
	s_add_u32 s18, s70, 0x4800
	s_addc_u32 s19, s71, 0
	s_add_u32 s20, s70, 0x4900
	s_addc_u32 s21, s71, 0
	s_add_u32 s26, s70, 0x4a00
	s_addc_u32 s27, s71, 0
	s_add_u32 s36, s70, 0x4b00
	s_addc_u32 s37, s71, 0
	s_add_u32 s38, s70, 0x4c00
	s_addc_u32 s39, s71, 0
	s_add_u32 s40, s70, 0x4d00
	s_addc_u32 s41, s71, 0
	s_add_u32 s42, s70, 0x4e00
	s_addc_u32 s43, s71, 0
	s_add_u32 s44, s70, 0x4f00
	s_addc_u32 s45, s71, 0
	s_add_u32 s48, s70, 0x5000
	s_addc_u32 s49, s71, 0
	s_add_u32 s52, s70, 0x5100
	s_addc_u32 s53, s71, 0
	s_add_u32 s54, s70, 0x5200
	s_addc_u32 s55, s71, 0
	s_mul_i32 s3, s31, s95
	s_add_u32 s56, s70, 0x5300
	s_mul_i32 s3, s3, s30
	s_addc_u32 s57, s71, 0
	s_mov_b32 s10, 1
	v_mov_b32_e32 v16, 0
	s_branch .LBB0_111

.LBB0_156:
	s_cmp_lt_i32 s28, 2
	s_cselect_b64 s[0:1], -1, 0
	s_and_b64 s[6:7], s[0:1], s[4:5]
	v_mov_b32_e32 v0, v196
	s_andn2_b64 vcc, exec, s[6:7]
	s_cbranch_vccnz .LBB0_203
	s_cmp_lt_i32 s2, 64
	s_cselect_b64 s[0:1], -1, 0
	s_cmp_lt_u32 s96, 64
	s_cselect_b64 s[4:5], -1, 0
	s_and_b64 s[0:1], s[0:1], s[4:5]
	s_andn2_b64 vcc, exec, s[0:1]
	s_cbranch_vccnz .LBB0_159
	s_mov_b32 s3, 0
	s_lshr_b32 s0, s2, 3
	s_and_b32 s4, s2, 7
	s_lshl_b32 s101, s4, 3
	s_add_i32 s101, s101, s0
	s_lshl_b32 s101, s101, 13
	s_ashr_i32 s1, s0, 31
	s_ashr_i32 s5, s4, 31
	s_lshl_b64 s[0:1], s[0:1], 2
	s_add_u32 s8, s70, s0
	s_addc_u32 s9, s71, s1
	s_lshl_b64 s[0:1], s[4:5], 16
	v_and_b32_e32 v38, 63, v0
	s_add_u32 s0, s8, s0
	v_lshlrev_b32_e32 v0, 10, v38
	v_mov_b32_e32 v1, 0
	s_addc_u32 s1, s9, s1
	v_lshl_add_u64 v[2:3], s[0:1], 0, v[0:1]
	s_mov_b64 s[0:1], 0x1900000
	v_lshl_add_u64 v[4:5], v[2:3], 0, s[0:1]
	s_mov_b32 s0, 0x1900000
	v_add_co_u32_e32 v2, vcc, s0, v2
	s_mov_b32 s8, s101
	s_mov_b32 s9, 0
	s_nop 0
	v_addc_co_u32_e32 v3, vcc, 0, v3, vcc
	global_load_dword v0, v[2:3], off
	global_load_dword v6, v[4:5], off offset:32
	global_load_dword v7, v[4:5], off offset:64
	global_load_dword v8, v[4:5], off offset:96
	global_load_dword v9, v[4:5], off offset:128
	global_load_dword v10, v[4:5], off offset:160
	global_load_dword v11, v[4:5], off offset:192
	global_load_dword v12, v[4:5], off offset:224
	global_load_dword v13, v[4:5], off offset:256
	global_load_dword v14, v[4:5], off offset:288
	global_load_dword v15, v[4:5], off offset:320
	global_load_dword v16, v[4:5], off offset:352
	global_load_dword v17, v[4:5], off offset:384
	global_load_dword v18, v[4:5], off offset:416
	global_load_dword v19, v[4:5], off offset:448
	global_load_dword v20, v[4:5], off offset:480
	global_load_dword v21, v[4:5], off offset:512
	global_load_dword v22, v[4:5], off offset:544
	global_load_dword v23, v[4:5], off offset:576
	global_load_dword v24, v[4:5], off offset:608
	global_load_dword v25, v[4:5], off offset:640
	global_load_dword v26, v[4:5], off offset:672
	global_load_dword v27, v[4:5], off offset:704
	global_load_dword v28, v[4:5], off offset:736
	global_load_dword v29, v[4:5], off offset:768
	global_load_dword v30, v[4:5], off offset:800
	global_load_dword v31, v[4:5], off offset:832
	global_load_dword v32, v[4:5], off offset:864
	global_load_dword v33, v[4:5], off offset:896
	global_load_dword v34, v[4:5], off offset:928
	global_load_dword v35, v[4:5], off offset:960
	global_load_dword v36, v[4:5], off offset:992
	v_mbcnt_lo_u32_b32 v2, -1, 0
	v_mbcnt_hi_u32_b32 v37, -1, v2
	v_and_b32_e32 v39, 64, v37
	v_add_u32_e32 v2, -1, v37
	v_cmp_lt_i32_e32 vcc, v2, v39
	v_add_u32_e32 v40, -2, v37
	v_add_u32_e32 v41, -4, v37
	v_cndmask_b32_e32 v2, v2, v37, vcc
	v_lshlrev_b32_e32 v44, 2, v2
	v_cmp_lt_i32_e32 vcc, v40, v39
	v_add_u32_e32 v42, -8, v37
	v_add_u32_e32 v43, -16, v37
	s_add_u32 s8, s70, s8
	s_addc_u32 s9, s71, s9
	s_mov_b32 s5, 0x1980000
	s_mov_b64 s[0:1], 0x1980000
	s_mov_b32 s4, 0x3fb8aa3b
	s_waitcnt vmcnt(31)
	v_add_f32_e32 v2, 0, v0
	s_waitcnt vmcnt(30)
	v_add_f32_e32 v3, v2, v6
	s_waitcnt vmcnt(29)
	v_add_f32_e32 v4, v3, v7
	s_waitcnt vmcnt(28)
	v_add_f32_e32 v5, v4, v8
	s_waitcnt vmcnt(27)
	v_add_f32_e32 v6, v5, v9
	s_waitcnt vmcnt(26)
	v_add_f32_e32 v7, v6, v10
	s_waitcnt vmcnt(25)
	v_add_f32_e32 v8, v7, v11
	s_waitcnt vmcnt(24)
	v_add_f32_e32 v9, v8, v12
	s_waitcnt vmcnt(23)
	v_add_f32_e32 v10, v9, v13
	s_waitcnt vmcnt(22)
	v_add_f32_e32 v11, v10, v14
	s_waitcnt vmcnt(21)
	v_add_f32_e32 v12, v11, v15
	s_waitcnt vmcnt(20)
	v_add_f32_e32 v13, v12, v16
	s_waitcnt vmcnt(19)
	v_add_f32_e32 v14, v13, v17
	s_waitcnt vmcnt(18)
	v_add_f32_e32 v15, v14, v18
	s_waitcnt vmcnt(17)
	v_add_f32_e32 v16, v15, v19
	s_waitcnt vmcnt(16)
	v_add_f32_e32 v17, v16, v20
	s_waitcnt vmcnt(15)
	v_add_f32_e32 v18, v17, v21
	s_waitcnt vmcnt(14)
	v_add_f32_e32 v19, v18, v22
	s_waitcnt vmcnt(13)
	v_add_f32_e32 v20, v19, v23
	s_waitcnt vmcnt(12)
	v_add_f32_e32 v21, v20, v24
	s_waitcnt vmcnt(11)
	v_add_f32_e32 v22, v21, v25
	s_waitcnt vmcnt(10)
	v_add_f32_e32 v23, v22, v26
	s_waitcnt vmcnt(9)
	v_add_f32_e32 v24, v23, v27
	s_waitcnt vmcnt(8)
	v_add_f32_e32 v25, v24, v28
	s_waitcnt vmcnt(7)
	v_add_f32_e32 v26, v25, v29
	s_waitcnt vmcnt(6)
	v_add_f32_e32 v27, v26, v30
	s_waitcnt vmcnt(5)
	v_add_f32_e32 v28, v27, v31
	s_waitcnt vmcnt(4)
	v_add_f32_e32 v29, v28, v32
	s_waitcnt vmcnt(3)
	v_add_f32_e32 v30, v29, v33
	s_waitcnt vmcnt(2)
	v_add_f32_e32 v31, v30, v34
	s_waitcnt vmcnt(1)
	v_add_f32_e32 v32, v31, v35
	s_waitcnt vmcnt(0)
	v_add_f32_e32 v33, v32, v36
	ds_bpermute_b32 v0, v44, v33
	v_cndmask_b32_e32 v35, v40, v37, vcc
	v_cmp_eq_u32_e32 vcc, 0, v38
	v_lshlrev_b32_e32 v35, 2, v35
	v_subrev_u32_e32 v34, 32, v37
	s_waitcnt lgkmcnt(0)
	v_add_f32_e32 v0, v33, v0
	v_cndmask_b32_e32 v0, v0, v33, vcc
	ds_bpermute_b32 v35, v35, v0
	v_cmp_lt_i32_e32 vcc, v41, v39
	s_waitcnt lgkmcnt(0)
	v_add_f32_e32 v35, v0, v35
	v_cndmask_b32_e32 v36, v41, v37, vcc
	v_cmp_lt_i32_e32 vcc, v42, v39
	v_lshlrev_b32_e32 v36, 2, v36
	s_nop 0
	v_cndmask_b32_e32 v40, v42, v37, vcc
	v_cmp_gt_u32_e32 vcc, 2, v38
	s_nop 1
	v_cndmask_b32_e32 v0, v35, v0, vcc
	ds_bpermute_b32 v35, v36, v0
	v_cmp_lt_i32_e32 vcc, v43, v39
	s_waitcnt lgkmcnt(0)
	v_add_f32_e32 v35, v0, v35
	v_cndmask_b32_e32 v36, v43, v37, vcc
	v_cmp_lt_i32_e32 vcc, v34, v39
	v_lshlrev_b32_e32 v36, 2, v36
	s_nop 0
	v_cndmask_b32_e32 v34, v34, v37, vcc
	v_cmp_gt_u32_e32 vcc, 4, v38
	v_lshlrev_b32_e32 v37, 2, v40
	s_nop 0
	v_cndmask_b32_e32 v0, v35, v0, vcc
	ds_bpermute_b32 v35, v37, v0
	v_lshlrev_b32_e32 v37, 2, v34
	v_cmp_gt_u32_e32 vcc, 8, v38
	s_waitcnt lgkmcnt(0)
	v_add_f32_e32 v34, v0, v35
	v_cndmask_b32_e32 v39, v34, v0, vcc
	ds_bpermute_b32 v36, v36, v39
	v_cmp_gt_u32_e32 vcc, 16, v38
	v_lshlrev_b32_e32 v0, 7, v38
	v_lshl_add_u64 v[0:1], s[8:9], 0, v[0:1]
	v_lshl_add_u64 v[34:35], v[0:1], 0, s[0:1]
	s_waitcnt lgkmcnt(0)
	v_add_f32_e32 v36, v39, v36
	v_cndmask_b32_e32 v39, v36, v39, vcc
	ds_bpermute_b32 v40, v37, v39
	v_add_co_u32_e32 v36, vcc, s5, v0
	s_waitcnt lgkmcnt(0)
	v_add_f32_e32 v0, v39, v40
	v_addc_co_u32_e32 v37, vcc, 0, v1, vcc
	v_cmp_gt_u32_e32 vcc, 32, v38
	s_nop 1
	v_cndmask_b32_e32 v0, v0, v39, vcc
	v_sub_f32_e32 v38, v0, v33
	v_pk_add_f32 v[0:1], v[2:3], v[38:39] op_sel_hi:[1,0]
	v_pk_add_f32 v[2:3], v[4:5], v[38:39] op_sel_hi:[1,0]
	v_pk_add_f32 v[4:5], v[6:7], v[38:39] op_sel_hi:[1,0]
	v_pk_add_f32 v[6:7], v[8:9], v[38:39] op_sel_hi:[1,0]
	v_pk_add_f32 v[8:9], v[10:11], v[38:39] op_sel_hi:[1,0]
	v_pk_add_f32 v[10:11], v[12:13], v[38:39] op_sel_hi:[1,0]
	v_pk_mul_f32 v[0:1], v[0:1], s[4:5] op_sel_hi:[1,0]
	v_pk_mul_f32 v[2:3], v[2:3], s[4:5] op_sel_hi:[1,0]
	v_pk_mul_f32 v[4:5], v[4:5], s[4:5] op_sel_hi:[1,0]
	v_pk_mul_f32 v[6:7], v[6:7], s[4:5] op_sel_hi:[1,0]
	v_pk_mul_f32 v[8:9], v[8:9], s[4:5] op_sel_hi:[1,0]
	v_pk_mul_f32 v[10:11], v[10:11], s[4:5] op_sel_hi:[1,0]
	global_store_dwordx4 v[36:37], v[0:3], off
	global_store_dwordx4 v[34:35], v[4:7], off offset:16
	global_store_dwordx4 v[34:35], v[8:11], off offset:32
	v_pk_add_f32 v[0:1], v[14:15], v[38:39] op_sel_hi:[1,0]
	v_pk_add_f32 v[2:3], v[16:17], v[38:39] op_sel_hi:[1,0]
	v_pk_mul_f32 v[0:1], v[0:1], s[4:5] op_sel_hi:[1,0]
	v_pk_mul_f32 v[2:3], v[2:3], s[4:5] op_sel_hi:[1,0]
	global_store_dwordx4 v[34:35], v[0:3], off offset:48
	s_nop 1
	v_pk_add_f32 v[0:1], v[18:19], v[38:39] op_sel_hi:[1,0]
	v_pk_add_f32 v[2:3], v[20:21], v[38:39] op_sel_hi:[1,0]
	v_pk_mul_f32 v[0:1], v[0:1], s[4:5] op_sel_hi:[1,0]
	v_pk_mul_f32 v[2:3], v[2:3], s[4:5] op_sel_hi:[1,0]
	global_store_dwordx4 v[34:35], v[0:3], off offset:64
	s_nop 1
	v_pk_add_f32 v[0:1], v[22:23], v[38:39] op_sel_hi:[1,0]
	v_pk_add_f32 v[2:3], v[24:25], v[38:39] op_sel_hi:[1,0]
	v_pk_mul_f32 v[0:1], v[0:1], s[4:5] op_sel_hi:[1,0]
	v_pk_mul_f32 v[2:3], v[2:3], s[4:5] op_sel_hi:[1,0]
	global_store_dwordx4 v[34:35], v[0:3], off offset:80
	s_nop 1
	v_pk_add_f32 v[0:1], v[26:27], v[38:39] op_sel_hi:[1,0]
	v_pk_add_f32 v[2:3], v[28:29], v[38:39] op_sel_hi:[1,0]
	v_pk_mul_f32 v[0:1], v[0:1], s[4:5] op_sel_hi:[1,0]
	v_pk_mul_f32 v[2:3], v[2:3], s[4:5] op_sel_hi:[1,0]
	global_store_dwordx4 v[34:35], v[0:3], off offset:96
	s_nop 1
	v_pk_add_f32 v[0:1], v[30:31], v[38:39] op_sel_hi:[1,0]
	v_pk_add_f32 v[2:3], v[32:33], v[38:39] op_sel_hi:[1,0]
	v_pk_mul_f32 v[0:1], v[0:1], s[4:5] op_sel_hi:[1,0]
	v_pk_mul_f32 v[2:3], v[2:3], s[4:5] op_sel_hi:[1,0]
	global_store_dwordx4 v[34:35], v[0:3], off offset:112

.LBB0_203:
	s_cmp_gt_i32 s29, 2
	s_cselect_b64 s[0:1], -1, 0
	s_and_b64 s[4:5], s[6:7], s[0:1]
	s_andn2_b64 vcc, exec, s[4:5]
	s_cbranch_vccnz .LBB0_253
	v_mov_b32_e32 v149, 0x4000
	global_load_dwordx4 v[140:143], v149, s[70:71] sc1
	global_load_dwordx4 v[144:147], v149, s[70:71] offset:16 sc1
	s_waitcnt vmcnt(0)
	v_cmp_eq_u32_e32 vcc, 0, v196
	s_waitcnt lgkmcnt(0)
	s_barrier
	s_and_saveexec_b64 s[4:5], vcc
	s_cbranch_execz .LBB0_252
	v_bcnt_u32_b32 v148, v140, 0
	v_bcnt_u32_b32 v148, v141, v148
	v_bcnt_u32_b32 v148, v142, v148
	v_bcnt_u32_b32 v148, v143, v148
	v_bcnt_u32_b32 v148, v144, v148
	v_bcnt_u32_b32 v148, v145, v148
	v_bcnt_u32_b32 v148, v146, v148
	v_bcnt_u32_b32 v148, v147, v148
	v_mov_b32_e32 v0, s94
	v_readfirstlane_b32 s100, v148
	s_cmp_eq_u32 s100, 8
	s_cselect_b32 s100, 1, 0
	s_waitcnt vmcnt(0) expcnt(0) lgkmcnt(0)
	ds_read_b32 v2, v0
	ds_read_b32 v0, v0 offset:4
	s_waitcnt lgkmcnt(1)
	v_cmp_ne_u32_e32 vcc, 0, v2
	s_cbranch_vccnz .LBB0_220
	s_add_u32 s6, s70, 0x4200
	s_addc_u32 s7, s71, 0
	s_add_u32 s8, s70, 0x4400
	s_addc_u32 s9, s71, 0
	s_add_u32 s12, s70, 0x4500
	s_addc_u32 s13, s71, 0
	s_add_u32 s14, s70, 0x4600
	s_addc_u32 s15, s71, 0
	s_add_u32 s16, s70, 0x4700
	s_addc_u32 s17, s71, 0
	s_add_u32 s18, s70, 0x4800
	s_addc_u32 s19, s71, 0
	s_add_u32 s20, s70, 0x4900
	s_addc_u32 s21, s71, 0
	s_add_u32 s26, s70, 0x4a00
	s_addc_u32 s27, s71, 0
	s_add_u32 s36, s70, 0x4b00
	s_addc_u32 s37, s71, 0
	s_add_u32 s38, s70, 0x4c00
	s_addc_u32 s39, s71, 0
	s_add_u32 s40, s70, 0x4d00
	s_addc_u32 s41, s71, 0
	s_add_u32 s42, s70, 0x4e00
	s_addc_u32 s43, s71, 0
	s_add_u32 s44, s70, 0x4f00
	s_addc_u32 s45, s71, 0
	s_add_u32 s48, s70, 0x5000
	s_addc_u32 s49, s71, 0
	s_add_u32 s52, s70, 0x5100
	s_addc_u32 s53, s71, 0
	s_add_u32 s54, s70, 0x5200
	s_addc_u32 s55, s71, 0
	s_mul_i32 s3, s31, s95
	s_add_u32 s56, s70, 0x5300
	s_mul_i32 s3, s3, s30
	s_addc_u32 s57, s71, 0
	s_mov_b32 s10, 1
	v_mov_b32_e32 v16, 0
	s_branch .LBB0_208

.LBB0_234:
	s_andn2_saveexec_b64 s[8:9], s[8:9]
	s_cbranch_execz .LBB0_252
	s_cmp_lg_u32 s100, 0
	s_cbranch_scc1 .Lxloc_1
	s_mov_b64 s[8:9], exec
	buffer_wbl2 sc1
	s_waitcnt lgkmcnt(0)
	s_waitcnt vmcnt(0)
	v_mbcnt_lo_u32_b32 v1, s8, 0
	v_mbcnt_hi_u32_b32 v1, s9, v1
	v_cmp_eq_u32_e32 vcc, 0, v1
	s_and_saveexec_b64 s[12:13], vcc
	s_cbranch_execz .LBB0_237
	s_bcnt1_i32_b64 s3, s[8:9]
	v_mov_b32_e32 v2, 0x7000
	v_mov_b32_e32 v3, s3
	global_atomic_add v2, v2, v3, s[70:71] offset:1024 sc0

.Lxloc_1:
	s_waitcnt lgkmcnt(0)
	v_mov_b32_e32 v0, 0x2000
	v_mov_b32_e32 v1, 1
	s_waitcnt vmcnt(0)
	buffer_inv sc1
	global_atomic_add v0, v1, s[6:7] offset:1024
	s_waitcnt vmcnt(0)

.LBB0_334:
	s_cmpk_gt_i32 s2, 0xff
	s_cbranch_scc1 .LBB0_343
	v_mbcnt_lo_u32_b32 v6, -1, 0
	v_mbcnt_hi_u32_b32 v6, -1, v6
	v_and_b32_e32 v8, 64, v6
	v_lshlrev_b32_e32 v1, 2, v197
	v_xor_b32_e32 v7, 32, v6
	v_add_u32_e32 v8, 64, v8
	v_and_b32_e32 v3, 16, v1
	v_lshrrev_b32_e32 v1, 1, v197
	s_add_u32 s4, s70, 0x1a00000
	s_mov_b32 s35, 0
	v_cmp_lt_i32_e32 vcc, v7, v8
	v_and_b32_e32 v0, 63, v197
	s_addc_u32 s5, s71, 0
	v_cndmask_b32_e32 v6, v6, v7, vcc
	s_lshl_b64 s[8:9], s[34:35], 7
	v_and_b32_e32 v7, 16, v1
	v_and_b32_e32 v2, 31, v197
	v_and_b32_e32 v4, 12, v1
	v_cmp_gt_u32_e64 s[0:1], 32, v0
	v_lshlrev_b32_e32 v114, 3, v0
	v_or_b32_e32 v0, s8, v7
	v_mov_b32_e32 v1, s9
	s_mov_b64 s[8:9], 0x7000000
	v_lshl_add_u64 v[116:117], v[0:1], 0, s[8:9]
	s_lshl_b64 s[8:9], s[34:35], 14
	v_lshlrev_b32_e32 v0, 5, v2
	v_and_b32_e32 v5, 3, v197
	v_lshlrev_b32_e32 v113, 2, v6
	v_lshlrev_b32_e32 v6, 1, v2
	v_or3_b32 v0, s8, v0, v7
	v_mov_b32_e32 v1, s9
	s_mov_b64 s[8:9], 0x1a80800
	v_or3_b32 v112, v4, v5, v3
	s_lshl_b32 s3, s34, 2
	v_or3_b32 v118, v3, v4, v5
	v_lshl_or_b32 v115, s34, 9, v6
	v_lshl_add_u64 v[120:121], v[0:1], 0, s[8:9]
	s_mov_b64 s[8:9], 0x8000
	v_mov_b32_e32 v122, 2.0
	s_mov_b64 s[12:13], 0x200
	s_mov_b64 s[14:15], 0x1000
	s_and_b32 s10, s2, 7
	s_lshl_b32 s10, s10, 5
	s_lshr_b32 s11, s2, 3
	s_add_i32 s10, s10, s11
	s_mov_b32 s11, s10
	s_branch .LBB0_337

.LBB0_393:
	s_cmp_lt_i32 s28, 4
	s_cselect_b64 s[4:5], -1, 0
	s_waitcnt lgkmcnt(0)
	s_and_b64 s[12:13], s[4:5], s[0:1]
	s_cmpk_lt_i32 s2, 0x100
	s_cselect_b64 s[8:9], -1, 0
	s_and_b64 s[0:1], s[12:13], s[8:9]
	v_mov_b32_e32 v0, v196
	s_andn2_b64 vcc, exec, s[0:1]
	s_cbranch_vccnz .LBB0_422
	v_and_b32_e32 v6, 63, v0
	v_and_b32_e32 v8, 31, v0
	s_add_i32 s14, 0, 0x21400
	v_lshlrev_b32_e32 v1, 2, v6
	v_lshlrev_b32_e32 v129, 1, v8
	v_add_u32_e32 v7, s14, v1
	s_add_u32 s16, s70, 0x1a00000
	v_lshl_or_b32 v4, s34, 9, v129
	v_and_b32_e32 v12, 16, v1
	v_mbcnt_lo_u32_b32 v1, -1, 0
	s_addc_u32 s17, s71, 0
	v_ashrrev_i32_e32 v5, 31, v4
	v_mbcnt_hi_u32_b32 v13, -1, v1
	v_lshl_add_u64 v[130:131], v[4:5], 2, s[16:17]
	v_bfe_u32 v143, v0, 5, 1
	v_and_b32_e32 v4, 64, v13
	v_lshlrev_b32_e32 v132, 5, v8
	v_mov_b32_e32 v133, 0
	v_add_u32_e32 v14, 64, v4
	v_lshl_add_u64 v[4:5], s[70:71], 0, v[132:133]
	v_lshlrev_b32_e32 v132, 4, v143
	s_mov_b32 s15, 0
	v_bfe_u32 v11, v0, 4, 2
	s_add_u32 s4, s70, 0x7000000
	v_xor_b32_e32 v1, 32, v13
	v_lshl_add_u64 v[4:5], v[4:5], 0, v[132:133]
	s_mov_b64 s[6:7], 0x1a80000
	s_mul_i32 s3, s34, 0x2200
	s_addc_u32 s5, s71, 0
	s_lshl_b32 s18, s34, 2
	s_mov_b32 s19, s15
	v_cmp_lt_i32_e32 vcc, v1, v14
	v_lshl_add_u64 v[134:135], v[4:5], 0, s[6:7]
	v_lshlrev_b32_e32 v4, 3, v11
	v_mov_b32_e32 v5, v133
	s_add_i32 s3, s3, 0
	v_cndmask_b32_e32 v1, v13, v1, vcc
	v_and_b32_e32 v136, 48, v0
	v_mov_b32_e32 v137, v133
	v_lshl_add_u64 v[144:145], s[4:5], 0, v[132:133]
	v_lshl_add_u64 v[146:147], s[4:5], 0, v[4:5]
	s_lshl_b64 s[4:5], s[18:19], 10
	v_and_b32_e32 v128, 15, v0
	v_lshrrev_b32_e32 v9, 1, v0
	v_and_b32_e32 v10, 3, v0
	v_lshlrev_b32_e32 v149, 2, v1
	v_lshl_add_u64 v[0:1], s[70:71], 0, v[136:137]
	s_mov_b64 s[6:7], 0x1ac0000
	s_add_u32 s4, s70, s4
	v_lshl_add_u64 v[138:139], v[0:1], 0, s[6:7]
	v_lshlrev_b32_e32 v0, 2, v8
	v_mul_u32_u24_e32 v1, 0x1100, v143
	s_addc_u32 s5, s71, s5
	v_lshlrev_b32_e32 v132, 4, v6
	v_lshl_add_u64 v[140:141], s[46:47], 0, v[136:137]
	v_add3_u32 v137, s3, v0, v1
	v_lshl_add_u64 v[0:1], s[4:5], 0, v[132:133]
	s_mov_b64 s[4:5], 0x500000
	v_lshl_add_u64 v[156:157], v[0:1], 0, s[4:5]
	s_mov_b64 s[4:5], 0x508000
	v_lshl_add_u64 v[158:159], v[0:1], 0, s[4:5]
	s_mov_b64 s[4:5], 0x508400
	v_lshl_add_u64 v[160:161], v[0:1], 0, s[4:5]
	s_mov_b64 s[4:5], 0x508800
	v_lshl_add_u64 v[162:163], v[0:1], 0, s[4:5]
	s_mov_b64 s[4:5], 0x508c00
	v_lshl_add_u64 v[164:165], v[0:1], 0, s[4:5]
	s_mov_b64 s[4:5], 0x510000
	v_lshl_add_u64 v[166:167], v[0:1], 0, s[4:5]
	s_mov_b64 s[4:5], 0x510400
	v_lshl_add_u64 v[168:169], v[0:1], 0, s[4:5]
	s_mov_b64 s[4:5], 0x510800
	v_lshl_add_u64 v[170:171], v[0:1], 0, s[4:5]
	s_mov_b64 s[4:5], 0x510c00
	v_lshl_add_u64 v[172:173], v[0:1], 0, s[4:5]
	s_mov_b64 s[4:5], 0x518000
	v_lshl_add_u64 v[174:175], v[0:1], 0, s[4:5]
	v_xor_b32_e32 v1, 16, v13
	v_lshlrev_b32_e32 v151, 2, v11
	s_and_b32 s6, s96, 0xffffffc0
	v_cmp_lt_i32_e32 vcc, v1, v14
	v_or_b32_e32 v0, s6, v151
	v_mov_b32_e32 v2, s50
	v_cndmask_b32_e32 v1, v13, v1, vcc
	v_mov_b32_e32 v3, s51
	v_lshlrev_b32_e32 v197, 2, v1
	v_ashrrev_i32_e32 v1, 31, v0
	v_lshl_add_u64 v[176:177], v[0:1], 2, v[2:3]
	v_lshlrev_b32_e32 v201, 1, v0
	v_xor_b32_e32 v0, 1, v13
	v_cmp_lt_i32_e32 vcc, v0, v14
	v_and_b32_e32 v9, 12, v9
	v_or3_b32 v142, v9, v10, v12
	v_cndmask_b32_e32 v0, v13, v0, vcc
	v_lshlrev_b32_e32 v212, 2, v0
	v_xor_b32_e32 v0, 2, v13
	v_cmp_lt_i32_e32 vcc, v0, v14
	v_add_u32_e32 v9, s3, v136
	s_lshl_b32 s36, s34, 8
	v_cndmask_b32_e32 v0, v13, v0, vcc
	s_add_i32 s3, 0, 0x11000
	v_lshlrev_b32_e32 v213, 2, v0
	v_xor_b32_e32 v0, 4, v13
	s_add_u32 s10, s70, 0x9000000
	v_cmp_lt_i32_e32 vcc, v0, v14
	s_addc_u32 s11, s71, 0
	s_ashr_i32 s7, s6, 31
	s_lshl_b32 s42, s34, 3
	v_cndmask_b32_e32 v0, v13, v0, vcc
	s_lshl_b64 s[20:21], s[18:19], 9
	v_lshlrev_b32_e32 v214, 2, v0
	v_xor_b32_e32 v0, 8, v13
	s_add_u32 s20, s70, s20
	v_cmp_lt_i32_e32 vcc, v0, v14
	s_addc_u32 s21, s71, s21
	s_lshl_b64 s[6:7], s[6:7], 1
	v_lshl_add_u64 v[178:179], s[10:11], 0, v[132:133]
	v_cndmask_b32_e32 v0, v13, v0, vcc
	v_lshlrev_b32_e32 v132, 3, v8
	s_add_u32 s6, s10, s6
	v_cmp_gt_u32_e64 s[0:1], 32, v6
	s_movk_i32 s26, 0x410
	v_or_b32_e32 v154, 48, v6
	v_cmp_gt_u32_e64 s[4:5], 16, v6
	v_mov_b32_e32 v6, s3
	v_lshlrev_b32_e32 v215, 2, v0
	v_lshl_add_u64 v[0:1], s[20:21], 0, v[132:133]
	s_mov_b64 s[20:21], 0x1c00000
	s_addc_u32 s7, s11, s7
	v_mul_u32_u24_e32 v10, 0x110, v128
	v_or_b32_e32 v148, 16, v128
	v_or_b32_e32 v152, 32, v128
	v_mad_u32_u24 v200, v128, s26, v6
	v_lshl_add_u64 v[180:181], v[0:1], 0, s[20:21]
	v_lshl_add_u64 v[182:183], s[6:7], 0, v[4:5]
	s_mov_b64 s[6:7], 0x1c00400
	s_mov_b32 s20, 0xffff0000
	v_mul_u32_u24_e32 v153, 0x410, v128
	v_or_b32_e32 v150, 32, v142
	v_mul_u32_u24_e32 v155, 0x410, v154
	v_or_b32_e32 v202, 32, v201
	v_or_b32_e32 v203, 64, v201
	v_or_b32_e32 v204, 0x60, v201
	v_add_u32_e32 v205, 0x4100, v200
	v_add_u32_e32 v206, 0x8200, v200
	v_mad_u32_u24 v207, v154, s26, v6
	v_lshl_add_u32 v208, v128, 2, s14
	v_lshl_add_u32 v209, v148, 2, s14
	v_lshl_add_u32 v210, v152, 2, s14
	v_lshl_add_u32 v211, v154, 2, s14
	v_not_b32_e32 v216, v143
	v_or_b32_e32 v217, 2, v143
	v_lshl_add_u64 v[184:185], v[0:1], 0, s[6:7]
	v_mad_u32_u24 v218, v154, s26, 0
	v_mad_u32_u24 v219, v128, s26, 0
	s_mov_b32 s21, -1
	v_add_u32_e32 v220, v9, v10
	s_mov_b32 s19, 0xffff0000
	s_mov_b64 s[26:27], 0x8000
	s_mov_b64 s[34:35], 0x10000
	v_mov_b32_e32 v221, 0x358637bd
	s_mov_b32 s43, 0xf800000
	v_mov_b32_e32 v222, 0x260
	s_movk_i32 s44, 0x1000
	s_movk_i32 s45, 0x2000
	s_movk_i32 s46, 0x3000
	s_movk_i32 s47, 0x7fff
	v_add_u32_e32 v223, s36, v7
	s_and_b32 s48, s2, 7
	s_lshl_b32 s48, s48, 5
	s_lshr_b32 s49, s2, 3
	s_add_i32 s48, s48, s49
	s_mov_b32 s49, 0
	s_mov_b32 s50, s48
	s_branch .LBB0_396

.LBB0_396:
	s_ashr_i32 s6, s50, 5
	s_and_b32 s10, s50, 31
	s_ashr_i32 s7, s6, 31
	v_cmp_gt_u32_e32 vcc, s10, v143
	v_mov_b32_e32 v45, v133
	v_mov_b32_e32 v44, v133
	v_mov_b32_e32 v43, v133
	v_mov_b32_e32 v42, v133
	v_mov_b32_e32 v39, v133
	v_mov_b32_e32 v38, v133
	v_mov_b32_e32 v35, v133
	v_mov_b32_e32 v34, v133
	v_mov_b32_e32 v47, v133
	v_mov_b32_e32 v46, v133
	v_mov_b32_e32 v41, v133
	v_mov_b32_e32 v40, v133
	v_mov_b32_e32 v33, v133
	v_mov_b32_e32 v32, v133
	v_mov_b32_e32 v31, v133
	v_mov_b32_e32 v30, v133
	s_and_saveexec_b64 s[36:37], vcc
	s_cbranch_execz .LBB0_404
	global_load_dwordx2 v[0:1], v[130:131], off offset:256
	global_load_dwordx2 v[2:3], v[130:131], off
	global_load_dwordx2 v[4:5], v[130:131], off offset:768
	global_load_dwordx2 v[6:7], v[130:131], off offset:512
	global_load_dwordx2 v[8:9], v[130:131], off offset:1280
	global_load_dwordx2 v[10:11], v[130:131], off offset:1024
	global_load_dwordx2 v[12:13], v[130:131], off offset:1536
	global_load_dwordx2 v[14:15], v[130:131], off offset:1792
	s_lshr_b32 s11, s2, 3
	s_and_b32 s11, s11, 31
	v_add_u32_e32 v48, s11, v216
	v_mov_b32_e32 v132, v133
	s_lshl_b64 s[40:41], s[6:7], 19
	v_mov_b32_e32 v52, v143
	v_mov_b64_e32 v[32:33], v[132:133]
	v_mov_b64_e32 v[40:41], v[132:133]
	v_mov_b64_e32 v[46:47], v[132:133]
	v_mov_b64_e32 v[34:35], v[132:133]
	v_mov_b64_e32 v[38:39], v[132:133]
	v_mov_b64_e32 v[42:43], v[132:133]
	v_mov_b64_e32 v[44:45], v[132:133]
	s_waitcnt vmcnt(7)
	v_mov_b32_e32 v16, v0
	s_waitcnt vmcnt(6)
	v_mov_b32_e32 v17, v2
	v_mov_b32_e32 v2, v1
	s_waitcnt vmcnt(4)
	v_mov_b32_e32 v1, v6
	v_mov_b32_e32 v6, v5
	s_waitcnt vmcnt(2)
	v_mov_b32_e32 v5, v10
	v_mov_b32_e32 v10, v9
	v_mov_b32_e32 v0, v4
	v_mov_b32_e32 v4, v8
	v_pk_mul_f32 v[8:9], v[2:3], v[2:3]
	v_pk_mul_f32 v[24:25], v[10:11], v[10:11]
	v_pk_add_f32 v[18:19], v[16:17], v[16:17]
	v_pk_mul_f32 v[20:21], v[6:7], v[6:7]
	v_pk_add_f32 v[22:23], v[0:1], v[0:1]
	v_pk_add_f32 v[26:27], v[4:5], v[4:5]
	v_pk_fma_f32 v[8:9], v[16:17], v[16:17], v[8:9] neg_lo:[0,0,1] neg_hi:[0,0,1]
	v_pk_fma_f32 v[4:5], v[4:5], v[4:5], v[24:25] neg_lo:[0,0,1] neg_hi:[0,0,1]
	v_pk_mul_f32 v[2:3], v[2:3], v[18:19]
	v_pk_fma_f32 v[0:1], v[0:1], v[0:1], v[20:21] neg_lo:[0,0,1] neg_hi:[0,0,1]
	v_pk_mul_f32 v[6:7], v[6:7], v[22:23]
	v_pk_mul_f32 v[10:11], v[10:11], v[26:27]
	v_pk_add_f32 v[18:19], v[8:9], v[8:9]
	v_pk_add_f32 v[26:27], v[4:5], v[4:5]
	v_pk_mul_f32 v[16:17], v[2:3], v[2:3]
	v_pk_mul_f32 v[20:21], v[6:7], v[6:7]
	v_pk_add_f32 v[22:23], v[0:1], v[0:1]
	v_pk_mul_f32 v[24:25], v[10:11], v[10:11]
	v_pk_mul_f32 v[2:3], v[2:3], v[18:19]
	v_pk_mul_f32 v[10:11], v[10:11], v[26:27]
	v_pk_fma_f32 v[8:9], v[8:9], v[8:9], v[16:17] neg_lo:[0,0,1] neg_hi:[0,0,1]
	v_pk_fma_f32 v[0:1], v[0:1], v[0:1], v[20:21] neg_lo:[0,0,1] neg_hi:[0,0,1]
	v_pk_mul_f32 v[6:7], v[6:7], v[22:23]
	v_pk_fma_f32 v[4:5], v[4:5], v[4:5], v[24:25] neg_lo:[0,0,1] neg_hi:[0,0,1]
	v_pk_mul_f32 v[16:17], v[2:3], v[2:3]
	v_pk_mul_f32 v[24:25], v[10:11], v[10:11]
	v_pk_add_f32 v[18:19], v[8:9], v[8:9]
	v_pk_mul_f32 v[20:21], v[6:7], v[6:7]
	v_pk_add_f32 v[22:23], v[0:1], v[0:1]
	v_pk_add_f32 v[26:27], v[4:5], v[4:5]
	v_pk_fma_f32 v[8:9], v[8:9], v[8:9], v[16:17] neg_lo:[0,0,1] neg_hi:[0,0,1]
	v_pk_fma_f32 v[4:5], v[4:5], v[4:5], v[24:25] neg_lo:[0,0,1] neg_hi:[0,0,1]
	v_pk_mul_f32 v[2:3], v[2:3], v[18:19]
	v_pk_fma_f32 v[0:1], v[0:1], v[0:1], v[20:21] neg_lo:[0,0,1] neg_hi:[0,0,1]
	v_pk_mul_f32 v[6:7], v[6:7], v[22:23]
	v_pk_mul_f32 v[10:11], v[10:11], v[26:27]
	v_pk_add_f32 v[18:19], v[8:9], v[8:9]
	v_pk_add_f32 v[26:27], v[4:5], v[4:5]
	v_pk_mul_f32 v[16:17], v[2:3], v[2:3]
	v_pk_mul_f32 v[20:21], v[6:7], v[6:7]
	v_pk_add_f32 v[22:23], v[0:1], v[0:1]
	v_pk_mul_f32 v[24:25], v[10:11], v[10:11]
	v_pk_mul_f32 v[2:3], v[2:3], v[18:19]
	v_pk_mul_f32 v[10:11], v[10:11], v[26:27]
	v_pk_fma_f32 v[8:9], v[8:9], v[8:9], v[16:17] neg_lo:[0,0,1] neg_hi:[0,0,1]
	v_pk_fma_f32 v[0:1], v[0:1], v[0:1], v[20:21] neg_lo:[0,0,1] neg_hi:[0,0,1]
	v_pk_mul_f32 v[6:7], v[6:7], v[22:23]
	v_pk_fma_f32 v[16:17], v[4:5], v[4:5], v[24:25] neg_lo:[0,0,1] neg_hi:[0,0,1]
	v_pk_mul_f32 v[4:5], v[2:3], v[2:3]
	v_pk_mul_f32 v[24:25], v[10:11], v[10:11]
	v_pk_add_f32 v[18:19], v[8:9], v[8:9]
	v_pk_mul_f32 v[20:21], v[6:7], v[6:7]
	v_pk_add_f32 v[22:23], v[0:1], v[0:1]
	v_pk_fma_f32 v[4:5], v[8:9], v[8:9], v[4:5] neg_lo:[0,0,1] neg_hi:[0,0,1]
	v_pk_fma_f32 v[8:9], v[16:17], v[16:17], v[24:25] neg_lo:[0,0,1] neg_hi:[0,0,1]
	v_pk_add_f32 v[16:17], v[16:17], v[16:17]
	v_pk_fma_f32 v[0:1], v[0:1], v[0:1], v[20:21] neg_lo:[0,0,1] neg_hi:[0,0,1]
	v_pk_mul_f32 v[6:7], v[6:7], v[22:23]
	v_pk_mul_f32 v[10:11], v[10:11], v[16:17]
	v_pk_mul_f32 v[22:23], v[6:7], v[6:7]
	v_pk_add_f32 v[24:25], v[0:1], v[0:1]
	v_pk_mul_f32 v[16:17], v[10:11], v[10:11]
	v_pk_fma_f32 v[28:29], v[0:1], v[0:1], v[22:23] neg_lo:[0,0,1] neg_hi:[0,0,1]
	v_pk_mul_f32 v[22:23], v[6:7], v[24:25]
	v_pk_fma_f32 v[24:25], v[8:9], v[8:9], v[16:17] neg_lo:[0,0,1] neg_hi:[0,0,1]
	s_waitcnt vmcnt(1)
	v_mov_b32_e32 v17, v12
	s_waitcnt vmcnt(0)
	v_mov_b32_e32 v12, v15
	v_mov_b32_e32 v16, v14
	v_pk_mul_f32 v[14:15], v[12:13], v[12:13]
	v_pk_mul_f32 v[2:3], v[2:3], v[18:19]
	v_pk_fma_f32 v[14:15], v[16:17], v[16:17], v[14:15] neg_lo:[0,0,1] neg_hi:[0,0,1]
	v_pk_add_f32 v[16:17], v[16:17], v[16:17]
	v_pk_mul_f32 v[18:19], v[2:3], v[2:3]
	v_pk_mul_f32 v[12:13], v[12:13], v[16:17]
	v_pk_fma_f32 v[30:31], v[4:5], v[4:5], v[18:19] neg_lo:[0,0,1] neg_hi:[0,0,1]
	v_pk_mul_f32 v[16:17], v[12:13], v[12:13]
	v_pk_add_f32 v[20:21], v[4:5], v[4:5]
	v_pk_fma_f32 v[16:17], v[14:15], v[14:15], v[16:17] neg_lo:[0,0,1] neg_hi:[0,0,1]
	v_pk_add_f32 v[14:15], v[14:15], v[14:15]
	v_pk_mul_f32 v[26:27], v[2:3], v[20:21]
	v_pk_mul_f32 v[12:13], v[12:13], v[14:15]
	v_pk_add_f32 v[8:9], v[8:9], v[8:9]
	v_pk_mul_f32 v[14:15], v[12:13], v[12:13]
	v_pk_mul_f32 v[0:1], v[26:27], v[26:27]
	v_pk_fma_f32 v[14:15], v[16:17], v[16:17], v[14:15] neg_lo:[0,0,1] neg_hi:[0,0,1]
	v_pk_add_f32 v[16:17], v[16:17], v[16:17]
	v_pk_add_f32 v[18:19], v[14:15], v[14:15]
	v_pk_mul_f32 v[12:13], v[12:13], v[16:17]
	v_pk_mul_f32 v[20:21], v[10:11], v[8:9]
	v_pk_mul_f32 v[16:17], v[12:13], v[12:13]
	v_pk_mul_f32 v[12:13], v[12:13], v[18:19]
	v_pk_fma_f32 v[14:15], v[14:15], v[14:15], v[16:17] neg_lo:[0,0,1] neg_hi:[0,0,1]
	v_pk_mul_f32 v[16:17], v[12:13], v[12:13]
	v_pk_add_f32 v[2:3], v[30:31], v[30:31]
	v_pk_fma_f32 v[16:17], v[14:15], v[14:15], v[16:17] neg_lo:[0,0,1] neg_hi:[0,0,1]
	v_pk_add_f32 v[14:15], v[14:15], v[14:15]
	v_pk_mul_f32 v[4:5], v[22:23], v[22:23]
	v_pk_mul_f32 v[12:13], v[12:13], v[14:15]
	v_pk_add_f32 v[6:7], v[28:29], v[28:29]
	v_pk_mul_f32 v[14:15], v[12:13], v[12:13]
	v_pk_fma_f32 v[0:1], v[30:31], v[30:31], v[0:1] neg_lo:[0,0,1] neg_hi:[0,0,1]
	v_pk_fma_f32 v[18:19], v[16:17], v[16:17], v[14:15] neg_lo:[0,0,1] neg_hi:[0,0,1]
	v_pk_add_f32 v[14:15], v[16:17], v[16:17]
	v_pk_mul_f32 v[8:9], v[20:21], v[20:21]
	v_pk_mul_f32 v[16:17], v[12:13], v[14:15]
	v_pk_add_f32 v[10:11], v[24:25], v[24:25]
	v_pk_mul_f32 v[12:13], v[16:17], v[16:17]
	v_pk_add_f32 v[14:15], v[18:19], v[18:19]
	v_cndmask_b32_e64 v36, v30, 1.0, s[0:1]
	v_and_b32_e32 v30, 2, v48
	v_pk_mul_f32 v[2:3], v[26:27], v[2:3]
	v_pk_fma_f32 v[4:5], v[28:29], v[28:29], v[4:5] neg_lo:[0,0,1] neg_hi:[0,0,1]
	v_pk_mul_f32 v[6:7], v[22:23], v[6:7]
	v_pk_fma_f32 v[8:9], v[24:25], v[24:25], v[8:9] neg_lo:[0,0,1] neg_hi:[0,0,1]
	v_pk_mul_f32 v[10:11], v[20:21], v[10:11]
	v_pk_fma_f32 v[12:13], v[18:19], v[18:19], v[12:13] neg_lo:[0,0,1] neg_hi:[0,0,1]
	v_pk_mul_f32 v[14:15], v[16:17], v[14:15]
	v_cndmask_b32_e64 v17, v17, 0, s[0:1]
	v_cndmask_b32_e64 v16, v16, 0, s[0:1]
	v_cndmask_b32_e64 v19, v19, 1.0, s[0:1]
	v_cndmask_b32_e64 v18, v18, 1.0, s[0:1]
	v_cndmask_b32_e64 v21, v21, 0, s[0:1]
	v_cndmask_b32_e64 v20, v20, 0, s[0:1]
	v_cndmask_b32_e64 v25, v25, 1.0, s[0:1]
	v_cndmask_b32_e64 v24, v24, 1.0, s[0:1]
	v_cndmask_b32_e64 v23, v23, 0, s[0:1]
	v_cndmask_b32_e64 v22, v22, 0, s[0:1]
	v_cndmask_b32_e64 v29, v29, 1.0, s[0:1]
	v_cndmask_b32_e64 v28, v28, 1.0, s[0:1]
	v_cndmask_b32_e64 v27, v27, 0, s[0:1]
	v_cndmask_b32_e64 v26, v26, 0, s[0:1]
	v_cndmask_b32_e64 v37, v31, 1.0, s[0:1]
	v_cmp_eq_u32_e32 vcc, 0, v30
	v_mov_b64_e32 v[30:31], v[132:133]
	s_and_saveexec_b64 s[38:39], vcc
	s_cbranch_execz .LBB0_399
	v_add_u32_e32 v32, s10, v216
	v_ashrrev_i32_e32 v33, 31, v32
	v_lshl_add_u64 v[30:31], v[180:181], 0, s[40:41]
	v_lshlrev_b64 v[32:33], 14, v[32:33]
	v_lshl_add_u64 v[30:31], v[30:31], 0, v[32:33]
	global_load_dwordx2 v[32:33], v[30:31], off offset:256
	global_load_dwordx2 v[34:35], v[30:31], off
	global_load_dwordx2 v[38:39], v[30:31], off offset:768
	global_load_dwordx2 v[40:41], v[30:31], off offset:512
	global_load_dwordx2 v[42:43], v[30:31], off offset:1280
	global_load_dwordx2 v[44:45], v[30:31], off offset:1024
	global_load_dwordx2 v[46:47], v[30:31], off offset:1792
	s_nop 0
	global_load_dwordx2 v[30:31], v[30:31], off offset:1536
	v_pk_mul_f32 v[54:55], v[0:1], v[26:27]
	v_pk_mul_f32 v[58:59], v[4:5], v[22:23]
	v_pk_mul_f32 v[62:63], v[8:9], v[20:21]
	v_pk_mul_f32 v[50:51], v[2:3], v[26:27]
	v_pk_mul_f32 v[56:57], v[6:7], v[22:23]
	v_pk_mul_f32 v[60:61], v[10:11], v[20:21]
	v_pk_mul_f32 v[64:65], v[14:15], v[16:17]
	v_pk_mul_f32 v[66:67], v[12:13], v[16:17]
	v_pk_fma_f32 v[50:51], v[0:1], v[36:37], v[50:51] neg_lo:[0,0,1] neg_hi:[0,0,1]
	v_pk_fma_f32 v[56:57], v[4:5], v[28:29], v[56:57] neg_lo:[0,0,1] neg_hi:[0,0,1]
	v_pk_fma_f32 v[60:61], v[8:9], v[24:25], v[60:61] neg_lo:[0,0,1] neg_hi:[0,0,1]
	v_pk_fma_f32 v[64:65], v[12:13], v[18:19], v[64:65] neg_lo:[0,0,1] neg_hi:[0,0,1]
	v_mov_b32_e32 v52, v217
	s_waitcnt vmcnt(7)
	v_mov_b32_e32 v68, v32
	s_waitcnt vmcnt(6)
	v_mov_b32_e32 v69, v34
	v_mov_b32_e32 v34, v33
	s_waitcnt vmcnt(5)
	v_mov_b32_e32 v32, v38
	s_waitcnt vmcnt(4)
	v_mov_b32_e32 v33, v40
	v_mov_b32_e32 v40, v39
	s_waitcnt vmcnt(3)
	v_mov_b32_e32 v38, v42
	s_waitcnt vmcnt(2)
	v_mov_b32_e32 v39, v44
	v_mov_b32_e32 v44, v43
	s_waitcnt vmcnt(1)
	v_mov_b32_e32 v42, v46
	s_waitcnt vmcnt(0)
	v_mov_b32_e32 v43, v30
	v_mov_b32_e32 v30, v47
	v_pk_mul_f32 v[46:47], v[26:27], v[34:35]
	v_pk_mul_f32 v[70:71], v[26:27], v[68:69]
	v_pk_fma_f32 v[26:27], v[2:3], v[36:37], v[54:55]
	v_pk_mul_f32 v[54:55], v[22:23], v[40:41]
	v_pk_mul_f32 v[72:73], v[22:23], v[32:33]
	v_pk_fma_f32 v[22:23], v[6:7], v[28:29], v[58:59]
	v_pk_mul_f32 v[58:59], v[20:21], v[44:45]
	v_pk_mul_f32 v[74:75], v[20:21], v[38:39]
	v_pk_fma_f32 v[20:21], v[10:11], v[24:25], v[62:63]
	v_pk_mul_f32 v[62:63], v[16:17], v[30:31]
	v_pk_mul_f32 v[76:77], v[16:17], v[42:43]
	v_pk_fma_f32 v[46:47], v[36:37], v[68:69], v[46:47] neg_lo:[0,0,1] neg_hi:[0,0,1]
	v_pk_fma_f32 v[34:35], v[36:37], v[34:35], v[70:71]
	v_pk_fma_f32 v[32:33], v[28:29], v[32:33], v[54:55] neg_lo:[0,0,1] neg_hi:[0,0,1]
	v_pk_fma_f32 v[36:37], v[28:29], v[40:41], v[72:73]
	v_pk_fma_f32 v[38:39], v[24:25], v[38:39], v[58:59] neg_lo:[0,0,1] neg_hi:[0,0,1]
	v_pk_fma_f32 v[54:55], v[24:25], v[44:45], v[74:75]
	v_pk_fma_f32 v[58:59], v[18:19], v[42:43], v[62:63] neg_lo:[0,0,1] neg_hi:[0,0,1]
	v_pk_fma_f32 v[30:31], v[18:19], v[30:31], v[76:77]
	v_pk_fma_f32 v[16:17], v[14:15], v[18:19], v[66:67]
	v_mov_b64_e32 v[18:19], v[64:65]
	v_mov_b64_e32 v[24:25], v[60:61]
	v_mov_b64_e32 v[28:29], v[56:57]
	v_pk_add_f32 v[44:45], v[46:47], 0 op_sel_hi:[1,0]
	v_pk_add_f32 v[46:47], v[34:35], 0 op_sel_hi:[1,0]
	v_pk_add_f32 v[42:43], v[32:33], 0 op_sel_hi:[1,0]
	v_pk_add_f32 v[40:41], v[36:37], 0 op_sel_hi:[1,0]
	v_pk_add_f32 v[38:39], v[38:39], 0 op_sel_hi:[1,0]
	v_pk_add_f32 v[32:33], v[54:55], 0 op_sel_hi:[1,0]
	v_pk_add_f32 v[34:35], v[58:59], 0 op_sel_hi:[1,0]
	v_pk_add_f32 v[30:31], v[30:31], 0 op_sel_hi:[1,0]
	v_mov_b64_e32 v[36:37], v[50:51]

.LBB0_453:
	s_andn2_saveexec_b64 s[10:11], s[12:13]
	s_cbranch_execz .LBB0_471
	s_cmp_lg_u32 s100, 0
	s_cbranch_scc1 .Lxloc_3
	s_mov_b64 s[12:13], exec
	buffer_wbl2 sc1
	s_waitcnt lgkmcnt(0)
	s_waitcnt vmcnt(0)
	v_mbcnt_lo_u32_b32 v1, s12, 0
	v_mbcnt_hi_u32_b32 v1, s13, v1
	v_cmp_eq_u32_e32 vcc, 0, v1
	s_and_saveexec_b64 s[14:15], vcc
	s_cbranch_execz .LBB0_456
	s_bcnt1_i32_b64 s3, s[12:13]
	v_mov_b32_e32 v2, 0x7000
	v_mov_b32_e32 v3, s3
	global_atomic_add v2, v2, v3, s[70:71] offset:1024 sc0

.Lxloc_4:
	s_waitcnt lgkmcnt(0)
	v_mov_b32_e32 v0, 0x2000
	v_mov_b32_e32 v1, 1
	s_waitcnt vmcnt(0)
	buffer_inv sc1
	global_atomic_add v0, v1, s[8:9] offset:1024
	s_waitcnt vmcnt(0)

.LBB0_628:
	s_andn2_saveexec_b64 s[10:11], s[10:11]
	s_cbranch_execz .LBB0_646
	s_cmp_lg_u32 s100, 0
	s_cbranch_scc1 .Lxloc_5
	s_mov_b64 s[10:11], exec
	buffer_wbl2 sc1
	s_waitcnt lgkmcnt(0)
	s_waitcnt vmcnt(0)
	v_mbcnt_lo_u32_b32 v1, s10, 0
	v_mbcnt_hi_u32_b32 v1, s11, v1
	v_cmp_eq_u32_e32 vcc, 0, v1
	s_and_saveexec_b64 s[12:13], vcc
	s_cbranch_execz .LBB0_631
	s_bcnt1_i32_b64 s3, s[10:11]
	v_mov_b32_e32 v2, 0x7000
	v_mov_b32_e32 v3, s3
	global_atomic_add v2, v2, v3, s[70:71] offset:1024 sc0
